# sample attention softmax: 32-lane row max / row sum via v_permlane16_swap + DPP row steps instead of ten ds_bpermute round trips
# baseline (speedup 1.0000x reference)
.LBB0_2021:
	s_or_b64 exec, exec, s[4:5]
	v_readlane_b32 s4, v254, 15
	v_readlane_b32 s5, v254, 16
	s_waitcnt lgkmcnt(0)
	s_barrier
	s_load_dwordx2 s[4:5], s[4:5], 0x80
	v_ashrrev_i32_e32 v201, 5, v8
	v_lshl_add_u32 v66, s14, 3, v201
	v_ashrrev_i32_e32 v67, 31, v66
	v_and_b32_e32 v96, 31, v12
	s_waitcnt lgkmcnt(0)
	v_lshl_add_u64 v[0:1], v[66:67], 2, s[4:5]
	v_readlane_b32 s4, v254, 45
	global_load_dword v67, v[0:1], off
	v_mov_b32_e32 v1, s91
	v_lshl_add_u32 v0, v201, 8, s4
	s_movk_i32 s4, 0x104
	v_mad_u32_u24 v203, v96, s4, v1
	v_add_u32_e32 v68, 0x2080, v203
	v_add_u32_e32 v69, 0x2088, v203
	v_add_u32_e32 v136, 0x2090, v203
	ds_read_b128 v[60:63], v0
	ds_read_b128 v[56:59], v0 offset:16
	ds_read_b128 v[52:55], v0 offset:32
	ds_read_b128 v[44:47], v0 offset:48
	ds_read2_b32 v[70:71], v203 offset1:1
	ds_read2_b32 v[72:73], v203 offset0:2 offset1:3
	ds_read2_b32 v[74:75], v203 offset0:4 offset1:5
	ds_read2_b32 v[76:77], v203 offset0:6 offset1:7
	ds_read2_b32 v[78:79], v203 offset0:8 offset1:9
	s_waitcnt vmcnt(12)
	ds_read2_b32 v[80:81], v203 offset0:10 offset1:11
	ds_read2_b32 v[82:83], v203 offset0:12 offset1:13
	s_waitcnt vmcnt(11)
	ds_read2_b32 v[84:85], v203 offset0:14 offset1:15
	ds_read_b128 v[48:51], v0 offset:64
	ds_read_b128 v[40:43], v0 offset:80
	ds_read2_b32 v[86:87], v203 offset0:16 offset1:17
	s_waitcnt vmcnt(10)
	ds_read2_b32 v[88:89], v203 offset0:18 offset1:19
	ds_read2_b32 v[90:91], v203 offset0:20 offset1:21
	s_waitcnt vmcnt(9)
	ds_read2_b32 v[92:93], v203 offset0:22 offset1:23
	ds_read_b128 v[36:39], v0 offset:96
	ds_read_b128 v[32:35], v0 offset:112
	ds_read2_b32 v[94:95], v203 offset0:24 offset1:25
	ds_read2_b32 v[98:99], v203 offset0:26 offset1:27
	ds_read2_b32 v[100:101], v203 offset0:28 offset1:29
	ds_read2_b32 v[102:103], v203 offset0:30 offset1:31
	ds_read_b128 v[28:31], v0 offset:128
	ds_read_b128 v[24:27], v0 offset:144
	ds_read2_b32 v[104:105], v203 offset0:32 offset1:33
	ds_read2_b32 v[106:107], v203 offset0:34 offset1:35
	ds_read2_b32 v[108:109], v203 offset0:36 offset1:37
	ds_read2_b32 v[110:111], v203 offset0:38 offset1:39
	ds_read_b128 v[20:23], v0 offset:160
	ds_read_b128 v[16:19], v0 offset:176
	ds_read2_b32 v[112:113], v203 offset0:40 offset1:41
	ds_read2_b32 v[114:115], v203 offset0:42 offset1:43
	ds_read2_b32 v[116:117], v203 offset0:44 offset1:45
	ds_read2_b32 v[118:119], v203 offset0:46 offset1:47
	ds_read_b128 v[12:15], v0 offset:192
	ds_read_b128 v[8:11], v0 offset:208
	ds_read2_b32 v[120:121], v203 offset0:48 offset1:49
	ds_read2_b32 v[122:123], v203 offset0:50 offset1:51
	ds_read2_b32 v[124:125], v203 offset0:52 offset1:53
	ds_read2_b32 v[126:127], v203 offset0:54 offset1:55
	ds_read_b128 v[4:7], v0 offset:224
	ds_read_b128 v[0:3], v0 offset:240
	ds_read2_b32 v[128:129], v203 offset0:56 offset1:57
	ds_read2_b32 v[130:131], v203 offset0:58 offset1:59
	ds_read2_b32 v[132:133], v203 offset0:60 offset1:61
	ds_read2_b32 v[134:135], v203 offset0:62 offset1:63
	v_add_u32_e32 v137, 0x2098, v203
	ds_read2_b32 v[196:197], v68 offset1:1
	ds_read2_b32 v[194:195], v69 offset1:1
	ds_read2_b32 v[190:191], v136 offset1:1
	ds_read2_b32 v[186:187], v137 offset1:1
	v_add_u32_e32 v68, 0x20a0, v203
	v_add_u32_e32 v69, 0x20a8, v203
	v_add_u32_e32 v136, 0x20b0, v203
	v_add_u32_e32 v137, 0x20b8, v203
	ds_read2_b32 v[192:193], v68 offset1:1
	ds_read2_b32 v[188:189], v69 offset1:1
	ds_read2_b32 v[182:183], v136 offset1:1
	ds_read2_b32 v[178:179], v137 offset1:1
	v_add_u32_e32 v68, 0x20c0, v203
	v_add_u32_e32 v69, 0x20c8, v203
	v_add_u32_e32 v136, 0x20d0, v203
	v_add_u32_e32 v137, 0x20d8, v203
	ds_read2_b32 v[184:185], v68 offset1:1
	ds_read2_b32 v[180:181], v69 offset1:1
	ds_read2_b32 v[174:175], v136 offset1:1
	ds_read2_b32 v[170:171], v137 offset1:1
	v_add_u32_e32 v68, 0x20e0, v203
	v_add_u32_e32 v69, 0x20e8, v203
	v_add_u32_e32 v136, 0x20f0, v203
	v_add_u32_e32 v137, 0x20f8, v203
	ds_read2_b32 v[176:177], v68 offset1:1
	ds_read2_b32 v[172:173], v69 offset1:1
	ds_read2_b32 v[166:167], v136 offset1:1
	ds_read2_b32 v[162:163], v137 offset1:1
	v_add_u32_e32 v68, 0x2100, v203
	v_add_u32_e32 v69, 0x2108, v203
	v_add_u32_e32 v136, 0x2110, v203
	v_add_u32_e32 v137, 0x2118, v203
	ds_read2_b32 v[168:169], v68 offset1:1
	ds_read2_b32 v[164:165], v69 offset1:1
	ds_read2_b32 v[158:159], v136 offset1:1
	ds_read2_b32 v[154:155], v137 offset1:1
	v_add_u32_e32 v68, 0x2120, v203
	v_add_u32_e32 v69, 0x2128, v203
	v_add_u32_e32 v136, 0x2130, v203
	v_add_u32_e32 v137, 0x2138, v203
	ds_read2_b32 v[160:161], v68 offset1:1
	ds_read2_b32 v[156:157], v69 offset1:1
	ds_read2_b32 v[150:151], v136 offset1:1
	ds_read2_b32 v[146:147], v137 offset1:1
	v_add_u32_e32 v68, 0x2140, v203
	v_add_u32_e32 v69, 0x2148, v203
	v_add_u32_e32 v136, 0x2150, v203
	v_add_u32_e32 v137, 0x2158, v203
	ds_read2_b32 v[152:153], v68 offset1:1
	ds_read2_b32 v[148:149], v69 offset1:1
	ds_read2_b32 v[142:143], v136 offset1:1
	ds_read2_b32 v[138:139], v137 offset1:1
	v_add_u32_e32 v68, 0x2160, v203
	v_add_u32_e32 v69, 0x2168, v203
	v_add_u32_e32 v136, 0x2170, v203
	v_add_u32_e32 v202, 0x2178, v203
	ds_read2_b32 v[144:145], v68 offset1:1
	ds_read2_b32 v[140:141], v69 offset1:1
	ds_read2_b32 v[136:137], v136 offset1:1
	ds_read2_b32 v[68:69], v202 offset1:1
	s_waitcnt lgkmcnt(14)
	v_fma_f32 v202, v60, v70, 0
	v_fmac_f32_e32 v202, v61, v71
	v_fmac_f32_e32 v202, v62, v72
	v_fmac_f32_e32 v202, v63, v73
	v_fmac_f32_e32 v202, v56, v74
	v_fmac_f32_e32 v202, v57, v75
	v_fmac_f32_e32 v202, v58, v76
	v_fmac_f32_e32 v202, v59, v77
	v_fma_f32 v196, v60, v196, 0
	v_fmac_f32_e32 v202, v52, v78
	v_fmac_f32_e32 v196, v61, v197
	v_fmac_f32_e32 v202, v53, v79
	v_fmac_f32_e32 v196, v62, v194
	v_fmac_f32_e32 v202, v54, v80
	v_fmac_f32_e32 v196, v63, v195
	v_fmac_f32_e32 v202, v55, v81
	v_fmac_f32_e32 v196, v56, v190
	v_fmac_f32_e32 v202, v44, v82
	v_fmac_f32_e32 v196, v57, v191
	v_fmac_f32_e32 v202, v45, v83
	v_fmac_f32_e32 v196, v58, v186
	v_fmac_f32_e32 v202, v46, v84
	v_fmac_f32_e32 v196, v59, v187
	v_fmac_f32_e32 v202, v47, v85
	v_fmac_f32_e32 v196, v52, v192
	v_fmac_f32_e32 v202, v48, v86
	v_fmac_f32_e32 v196, v53, v193
	v_fmac_f32_e32 v202, v49, v87
	v_fmac_f32_e32 v196, v54, v188
	v_fmac_f32_e32 v202, v50, v88
	v_fmac_f32_e32 v196, v55, v189
	v_fmac_f32_e32 v202, v51, v89
	v_fmac_f32_e32 v196, v44, v182
	v_fmac_f32_e32 v202, v40, v90
	v_fmac_f32_e32 v196, v45, v183
	v_fmac_f32_e32 v202, v41, v91
	v_fmac_f32_e32 v196, v46, v178
	v_fmac_f32_e32 v202, v42, v92
	v_fmac_f32_e32 v196, v47, v179
	v_fmac_f32_e32 v202, v43, v93
	v_fmac_f32_e32 v196, v48, v184
	v_fmac_f32_e32 v202, v36, v94
	v_fmac_f32_e32 v196, v49, v185
	v_fmac_f32_e32 v202, v37, v95
	v_fmac_f32_e32 v196, v50, v180
	v_fmac_f32_e32 v202, v38, v98
	v_fmac_f32_e32 v196, v51, v181
	v_fmac_f32_e32 v202, v39, v99
	v_fmac_f32_e32 v196, v40, v174
	v_fmac_f32_e32 v202, v32, v100
	v_fmac_f32_e32 v196, v41, v175
	v_fmac_f32_e32 v202, v33, v101
	v_fmac_f32_e32 v196, v42, v170
	v_fmac_f32_e32 v202, v34, v102
	v_fmac_f32_e32 v196, v43, v171
	v_fmac_f32_e32 v202, v35, v103
	v_fmac_f32_e32 v196, v36, v176
	v_fmac_f32_e32 v202, v28, v104
	v_fmac_f32_e32 v196, v37, v177
	v_fmac_f32_e32 v202, v29, v105
	v_fmac_f32_e32 v196, v38, v172
	v_fmac_f32_e32 v202, v30, v106
	v_fmac_f32_e32 v196, v39, v173
	v_fmac_f32_e32 v202, v31, v107
	v_fmac_f32_e32 v196, v32, v166
	v_fmac_f32_e32 v202, v24, v108
	v_fmac_f32_e32 v196, v33, v167
	v_fmac_f32_e32 v202, v25, v109
	v_fmac_f32_e32 v196, v34, v162
	v_fmac_f32_e32 v202, v26, v110
	v_fmac_f32_e32 v196, v35, v163
	v_fmac_f32_e32 v202, v27, v111
	v_fmac_f32_e32 v196, v28, v168
	v_fmac_f32_e32 v202, v20, v112
	v_fmac_f32_e32 v196, v29, v169
	v_fmac_f32_e32 v202, v21, v113
	v_fmac_f32_e32 v196, v30, v164
	v_fmac_f32_e32 v202, v22, v114
	v_fmac_f32_e32 v196, v31, v165
	v_fmac_f32_e32 v202, v23, v115
	s_waitcnt lgkmcnt(13)
	v_fmac_f32_e32 v196, v24, v158
	v_fmac_f32_e32 v202, v16, v116
	v_fmac_f32_e32 v196, v25, v159
	v_fmac_f32_e32 v202, v17, v117
	s_waitcnt lgkmcnt(12)
	v_fmac_f32_e32 v196, v26, v154
	v_fmac_f32_e32 v202, v18, v118
	v_fmac_f32_e32 v196, v27, v155
	v_fmac_f32_e32 v202, v19, v119
	s_waitcnt lgkmcnt(11)
	v_fmac_f32_e32 v196, v20, v160
	v_fmac_f32_e32 v202, v12, v120
	v_fmac_f32_e32 v196, v21, v161
	v_fmac_f32_e32 v202, v13, v121
	s_waitcnt lgkmcnt(10)
	v_fmac_f32_e32 v196, v22, v156
	v_fmac_f32_e32 v202, v14, v122
	v_fmac_f32_e32 v196, v23, v157
	v_fmac_f32_e32 v202, v15, v123
	s_waitcnt lgkmcnt(9)
	v_fmac_f32_e32 v196, v16, v150
	v_fmac_f32_e32 v202, v8, v124
	v_fmac_f32_e32 v196, v17, v151
	v_fmac_f32_e32 v202, v9, v125
	s_waitcnt lgkmcnt(8)
	v_fmac_f32_e32 v196, v18, v146
	v_fmac_f32_e32 v202, v10, v126
	v_fmac_f32_e32 v196, v19, v147
	v_fmac_f32_e32 v202, v11, v127
	s_waitcnt lgkmcnt(7)
	v_fmac_f32_e32 v196, v12, v152
	v_fmac_f32_e32 v202, v4, v128
	v_fmac_f32_e32 v196, v13, v153
	v_fmac_f32_e32 v202, v5, v129
	s_waitcnt lgkmcnt(6)
	v_fmac_f32_e32 v196, v14, v148
	v_fmac_f32_e32 v202, v6, v130
	v_fmac_f32_e32 v196, v15, v149
	v_fmac_f32_e32 v202, v7, v131
	s_waitcnt lgkmcnt(5)
	v_fmac_f32_e32 v196, v8, v142
	v_fmac_f32_e32 v202, v0, v132
	v_fmac_f32_e32 v196, v9, v143
	v_fmac_f32_e32 v202, v1, v133
	s_waitcnt lgkmcnt(4)
	v_fmac_f32_e32 v196, v10, v138
	v_fmac_f32_e32 v202, v2, v134
	v_add_u32_e32 v70, 0x4100, v203
	v_add_u32_e32 v71, 0x4108, v203
	v_add_u32_e32 v72, 0x4110, v203
	v_fmac_f32_e32 v196, v11, v139
	v_fmac_f32_e32 v202, v3, v135
	v_add_u32_e32 v73, 0x4118, v203
	ds_read2_b32 v[134:135], v70 offset1:1
	ds_read2_b32 v[132:133], v71 offset1:1
	ds_read2_b32 v[128:129], v72 offset1:1
	ds_read2_b32 v[124:125], v73 offset1:1
	v_add_u32_e32 v70, 0x4120, v203
	v_add_u32_e32 v71, 0x4128, v203
	v_add_u32_e32 v72, 0x4130, v203
	s_waitcnt lgkmcnt(7)
	v_fmac_f32_e32 v196, v4, v144
	v_add_u32_e32 v73, 0x4138, v203
	ds_read2_b32 v[130:131], v70 offset1:1
	ds_read2_b32 v[126:127], v71 offset1:1
	ds_read2_b32 v[120:121], v72 offset1:1
	ds_read2_b32 v[116:117], v73 offset1:1
	v_add_u32_e32 v70, 0x4140, v203
	v_add_u32_e32 v71, 0x4148, v203
	v_add_u32_e32 v72, 0x4150, v203
	v_fmac_f32_e32 v196, v5, v145
	v_add_u32_e32 v73, 0x4158, v203
	ds_read2_b32 v[122:123], v70 offset1:1
	ds_read2_b32 v[118:119], v71 offset1:1
	ds_read2_b32 v[112:113], v72 offset1:1
	ds_read2_b32 v[108:109], v73 offset1:1
	v_add_u32_e32 v70, 0x4160, v203
	v_add_u32_e32 v71, 0x4168, v203
	v_add_u32_e32 v72, 0x4170, v203
	s_waitcnt lgkmcnt(14)
	v_fmac_f32_e32 v196, v6, v140
	v_add_u32_e32 v73, 0x4178, v203
	ds_read2_b32 v[114:115], v70 offset1:1
	ds_read2_b32 v[110:111], v71 offset1:1
	ds_read2_b32 v[104:105], v72 offset1:1
	ds_read2_b32 v[100:101], v73 offset1:1
	v_add_u32_e32 v70, 0x4180, v203
	v_add_u32_e32 v71, 0x4188, v203
	v_add_u32_e32 v72, 0x4190, v203
	v_fmac_f32_e32 v196, v7, v141
	v_add_u32_e32 v73, 0x4198, v203
	ds_read2_b32 v[106:107], v70 offset1:1
	ds_read2_b32 v[102:103], v71 offset1:1
	ds_read2_b32 v[94:95], v72 offset1:1
	ds_read2_b32 v[90:91], v73 offset1:1
	v_add_u32_e32 v70, 0x41a0, v203
	v_add_u32_e32 v71, 0x41a8, v203
	v_add_u32_e32 v72, 0x41b0, v203
	s_waitcnt lgkmcnt(14)
	v_fmac_f32_e32 v196, v0, v136
	v_add_u32_e32 v73, 0x41b8, v203
	ds_read2_b32 v[98:99], v70 offset1:1
	ds_read2_b32 v[92:93], v71 offset1:1
	ds_read2_b32 v[86:87], v72 offset1:1
	ds_read2_b32 v[82:83], v73 offset1:1
	v_add_u32_e32 v70, 0x41c0, v203
	v_add_u32_e32 v71, 0x41c8, v203
	v_add_u32_e32 v72, 0x41d0, v203
	v_fmac_f32_e32 v196, v1, v137
	v_add_u32_e32 v73, 0x41d8, v203
	ds_read2_b32 v[88:89], v70 offset1:1
	ds_read2_b32 v[84:85], v71 offset1:1
	ds_read2_b32 v[78:79], v72 offset1:1
	ds_read2_b32 v[74:75], v73 offset1:1
	v_add_u32_e32 v70, 0x41e0, v203
	v_add_u32_e32 v71, 0x41e8, v203
	v_add_u32_e32 v72, 0x41f0, v203
	v_fmac_f32_e32 v196, v2, v68
	v_add_u32_e32 v68, 0x6180, v203
	v_add_u32_e32 v204, 0x41f8, v203
	ds_read2_b32 v[80:81], v70 offset1:1
	ds_read2_b32 v[76:77], v71 offset1:1
	ds_read2_b32 v[72:73], v72 offset1:1
	ds_read2_b32 v[70:71], v204 offset1:1
	ds_read2_b32 v[136:137], v68 offset1:1
	v_add_u32_e32 v68, 0x6188, v203
	v_add_u32_e32 v140, 0x6190, v203
	v_add_u32_e32 v142, 0x6198, v203
	ds_read2_b32 v[138:139], v68 offset1:1
	ds_read2_b32 v[140:141], v140 offset1:1
	ds_read2_b32 v[142:143], v142 offset1:1
	s_waitcnt lgkmcnt(3)
	v_fma_f32 v68, v60, v136, 0
	v_fma_f32 v60, v60, v134, 0
	v_fmac_f32_e32 v68, v61, v137
	v_fmac_f32_e32 v60, v61, v135
	s_waitcnt lgkmcnt(2)
	v_fmac_f32_e32 v68, v62, v138
	v_add_u32_e32 v136, 0x61a0, v203
	v_fmac_f32_e32 v60, v62, v132
	v_fmac_f32_e32 v68, v63, v139
	ds_read2_b32 v[136:137], v136 offset1:1
	v_fmac_f32_e32 v60, v63, v133
	s_waitcnt lgkmcnt(2)
	v_fmac_f32_e32 v68, v56, v140
	v_fmac_f32_e32 v60, v56, v128
	v_fmac_f32_e32 v68, v57, v141
	v_fmac_f32_e32 v60, v57, v129
	s_waitcnt lgkmcnt(1)
	v_fmac_f32_e32 v68, v58, v142
	v_add_u32_e32 v138, 0x61a8, v203
	v_add_u32_e32 v140, 0x61b0, v203
	v_add_u32_e32 v142, 0x61b8, v203
	v_fmac_f32_e32 v60, v58, v124
	v_fmac_f32_e32 v68, v59, v143
	ds_read2_b32 v[138:139], v138 offset1:1
	ds_read2_b32 v[140:141], v140 offset1:1
	ds_read2_b32 v[142:143], v142 offset1:1
	v_fmac_f32_e32 v60, v59, v125
	s_waitcnt lgkmcnt(3)
	v_fmac_f32_e32 v68, v52, v136
	v_fmac_f32_e32 v60, v52, v130
	v_fmac_f32_e32 v68, v53, v137
	v_fmac_f32_e32 v60, v53, v131
	s_waitcnt lgkmcnt(2)
	v_fmac_f32_e32 v68, v54, v138
	v_add_u32_e32 v136, 0x61c0, v203
	v_fmac_f32_e32 v60, v54, v126
	v_fmac_f32_e32 v68, v55, v139
	ds_read2_b32 v[136:137], v136 offset1:1
	v_fmac_f32_e32 v60, v55, v127
	s_waitcnt lgkmcnt(2)
	v_fmac_f32_e32 v68, v44, v140
	v_fmac_f32_e32 v60, v44, v120
	v_fmac_f32_e32 v68, v45, v141
	v_fmac_f32_e32 v60, v45, v121
	s_waitcnt lgkmcnt(1)
	v_fmac_f32_e32 v68, v46, v142
	v_add_u32_e32 v138, 0x61c8, v203
	v_add_u32_e32 v140, 0x61d0, v203
	v_add_u32_e32 v142, 0x61d8, v203
	v_fmac_f32_e32 v60, v46, v116
	v_fmac_f32_e32 v68, v47, v143
	ds_read2_b32 v[138:139], v138 offset1:1
	ds_read2_b32 v[140:141], v140 offset1:1
	ds_read2_b32 v[142:143], v142 offset1:1
	v_fmac_f32_e32 v60, v47, v117
	s_waitcnt lgkmcnt(3)
	v_fmac_f32_e32 v68, v48, v136
	v_fmac_f32_e32 v60, v48, v122
	v_fmac_f32_e32 v68, v49, v137
	v_fmac_f32_e32 v60, v49, v123
	s_waitcnt lgkmcnt(2)
	v_fmac_f32_e32 v68, v50, v138
	v_add_u32_e32 v136, 0x61e0, v203
	v_fmac_f32_e32 v60, v50, v118
	v_fmac_f32_e32 v68, v51, v139
	ds_read2_b32 v[136:137], v136 offset1:1
	v_fmac_f32_e32 v60, v51, v119
	s_waitcnt lgkmcnt(2)
	v_fmac_f32_e32 v68, v40, v140
	v_fmac_f32_e32 v60, v40, v112
	v_fmac_f32_e32 v68, v41, v141
	v_fmac_f32_e32 v60, v41, v113
	s_waitcnt lgkmcnt(1)
	v_fmac_f32_e32 v68, v42, v142
	v_add_u32_e32 v138, 0x61e8, v203
	v_add_u32_e32 v140, 0x61f0, v203
	v_add_u32_e32 v142, 0x61f8, v203
	v_fmac_f32_e32 v60, v42, v108
	v_fmac_f32_e32 v68, v43, v143
	ds_read2_b32 v[138:139], v138 offset1:1
	ds_read2_b32 v[140:141], v140 offset1:1
	ds_read2_b32 v[142:143], v142 offset1:1
	v_fmac_f32_e32 v60, v43, v109
	s_waitcnt lgkmcnt(3)
	v_fmac_f32_e32 v68, v36, v136
	v_fmac_f32_e32 v60, v36, v114
	v_fmac_f32_e32 v68, v37, v137
	v_fmac_f32_e32 v60, v37, v115
	s_waitcnt lgkmcnt(2)
	v_fmac_f32_e32 v68, v38, v138
	v_add_u32_e32 v136, 0x6200, v203
	v_fmac_f32_e32 v60, v38, v110
	v_fmac_f32_e32 v68, v39, v139
	ds_read2_b32 v[136:137], v136 offset1:1
	v_fmac_f32_e32 v60, v39, v111
	s_waitcnt lgkmcnt(2)
	v_fmac_f32_e32 v68, v32, v140
	v_fmac_f32_e32 v60, v32, v104
	v_fmac_f32_e32 v68, v33, v141
	v_fmac_f32_e32 v60, v33, v105
	s_waitcnt lgkmcnt(1)
	v_fmac_f32_e32 v68, v34, v142
	v_add_u32_e32 v138, 0x6208, v203
	v_add_u32_e32 v140, 0x6210, v203
	v_add_u32_e32 v142, 0x6218, v203
	v_fmac_f32_e32 v60, v34, v100
	v_fmac_f32_e32 v68, v35, v143
	ds_read2_b32 v[138:139], v138 offset1:1
	ds_read2_b32 v[140:141], v140 offset1:1
	ds_read2_b32 v[142:143], v142 offset1:1
	v_fmac_f32_e32 v60, v35, v101
	s_waitcnt lgkmcnt(3)
	v_fmac_f32_e32 v68, v28, v136
	v_fmac_f32_e32 v60, v28, v106
	v_fmac_f32_e32 v68, v29, v137
	v_fmac_f32_e32 v60, v29, v107
	s_waitcnt lgkmcnt(2)
	v_fmac_f32_e32 v68, v30, v138
	v_add_u32_e32 v136, 0x6220, v203
	v_fmac_f32_e32 v60, v30, v102
	v_fmac_f32_e32 v68, v31, v139
	ds_read2_b32 v[136:137], v136 offset1:1
	v_fmac_f32_e32 v60, v31, v103
	s_waitcnt lgkmcnt(2)
	v_fmac_f32_e32 v68, v24, v140
	v_fmac_f32_e32 v60, v24, v94
	v_fmac_f32_e32 v68, v25, v141
	v_fmac_f32_e32 v60, v25, v95
	s_waitcnt lgkmcnt(1)
	v_fmac_f32_e32 v68, v26, v142
	v_add_u32_e32 v138, 0x6228, v203
	v_add_u32_e32 v140, 0x6230, v203
	v_add_u32_e32 v142, 0x6238, v203
	v_fmac_f32_e32 v60, v26, v90
	v_fmac_f32_e32 v68, v27, v143
	ds_read2_b32 v[138:139], v138 offset1:1
	ds_read2_b32 v[140:141], v140 offset1:1
	ds_read2_b32 v[142:143], v142 offset1:1
	v_fmac_f32_e32 v60, v27, v91
	s_waitcnt lgkmcnt(3)
	v_fmac_f32_e32 v68, v20, v136
	v_fmac_f32_e32 v60, v20, v98
	v_fmac_f32_e32 v68, v21, v137
	v_fmac_f32_e32 v60, v21, v99
	s_waitcnt lgkmcnt(2)
	v_fmac_f32_e32 v68, v22, v138
	v_add_u32_e32 v136, 0x6240, v203
	v_fmac_f32_e32 v60, v22, v92
	v_fmac_f32_e32 v68, v23, v139
	ds_read2_b32 v[136:137], v136 offset1:1
	v_fmac_f32_e32 v60, v23, v93
	s_waitcnt lgkmcnt(2)
	v_fmac_f32_e32 v68, v16, v140
	v_fmac_f32_e32 v60, v16, v86
	v_fmac_f32_e32 v68, v17, v141
	v_fmac_f32_e32 v60, v17, v87
	s_waitcnt lgkmcnt(1)
	v_fmac_f32_e32 v68, v18, v142
	v_add_u32_e32 v138, 0x6248, v203
	v_add_u32_e32 v140, 0x6250, v203
	v_add_u32_e32 v142, 0x6258, v203
	v_fmac_f32_e32 v60, v18, v82
	v_fmac_f32_e32 v68, v19, v143
	ds_read2_b32 v[138:139], v138 offset1:1
	ds_read2_b32 v[140:141], v140 offset1:1
	ds_read2_b32 v[142:143], v142 offset1:1
	v_fmac_f32_e32 v60, v19, v83
	s_waitcnt lgkmcnt(3)
	v_fmac_f32_e32 v68, v12, v136
	v_fmac_f32_e32 v60, v12, v88
	v_fmac_f32_e32 v68, v13, v137
	v_fmac_f32_e32 v60, v13, v89
	s_waitcnt lgkmcnt(2)
	v_fmac_f32_e32 v68, v14, v138
	v_add_u32_e32 v136, 0x6260, v203
	v_fmac_f32_e32 v60, v14, v84
	v_fmac_f32_e32 v68, v15, v139
	ds_read2_b32 v[136:137], v136 offset1:1
	v_fmac_f32_e32 v60, v15, v85
	s_waitcnt lgkmcnt(2)
	v_fmac_f32_e32 v68, v8, v140
	v_fmac_f32_e32 v60, v8, v78
	v_fmac_f32_e32 v68, v9, v141
	v_fmac_f32_e32 v60, v9, v79
	s_waitcnt lgkmcnt(1)
	v_fmac_f32_e32 v68, v10, v142
	v_add_u32_e32 v138, 0x6268, v203
	v_add_u32_e32 v140, 0x6270, v203
	v_add_u32_e32 v142, 0x6278, v203
	v_fmac_f32_e32 v60, v10, v74
	v_fmac_f32_e32 v68, v11, v143
	ds_read2_b32 v[138:139], v138 offset1:1
	ds_read2_b32 v[140:141], v140 offset1:1
	ds_read2_b32 v[142:143], v142 offset1:1
	v_fmac_f32_e32 v60, v11, v75
	s_waitcnt lgkmcnt(3)
	v_fmac_f32_e32 v68, v4, v136
	v_fmac_f32_e32 v60, v4, v80
	v_fmac_f32_e32 v68, v5, v137
	v_fmac_f32_e32 v60, v5, v81
	s_waitcnt lgkmcnt(2)
	v_fmac_f32_e32 v68, v6, v138
	v_fmac_f32_e32 v60, v6, v76
	v_fmac_f32_e32 v68, v7, v139
	v_fmac_f32_e32 v60, v7, v77
	s_waitcnt lgkmcnt(1)
	v_fmac_f32_e32 v68, v0, v140
	v_fmac_f32_e32 v60, v0, v72
	v_fmac_f32_e32 v68, v1, v141
	v_fmac_f32_e32 v60, v1, v73
	v_and_b32_e32 v1, 64, v198
	s_waitcnt lgkmcnt(0)
	v_fmac_f32_e32 v68, v2, v142
	v_fmac_f32_e32 v60, v2, v70
	v_add_u32_e32 v1, 64, v1
	v_xor_b32_e32 v2, 16, v198
	v_fmac_f32_e32 v196, v3, v69
	v_cmp_lt_i32_e32 vcc, v2, v1
	v_fmac_f32_e32 v68, v3, v143
	v_fmac_f32_e32 v60, v3, v71
	s_waitcnt vmcnt(0)
	v_max3_f32 v0, v67, v202, v196
	v_cndmask_b32_e32 v2, v198, v2, vcc
	v_max3_f32 v0, v0, v60, v68
	v_lshlrev_b32_e32 v2, 2, v2
	v_mov_b32_e32 v3, v0
	v_mov_b32_e32 v4, v0
	s_nop 1
	v_permlane16_swap_b32_e32 v3, v4
	v_max_f32_e32 v0, v3, v4
	s_nop 1
	v_max_f32_dpp v0, v0, v0 quad_perm:[1,0,3,2] row_mask:0xf bank_mask:0xf
	s_nop 1
	v_max_f32_dpp v0, v0, v0 quad_perm:[2,3,0,1] row_mask:0xf bank_mask:0xf
	s_nop 1
	v_max_f32_dpp v0, v0, v0 row_half_mirror row_mask:0xf bank_mask:0xf
	s_nop 1
	v_max_f32_dpp v0, v0, v0 row_mirror row_mask:0xf bank_mask:0xf
	v_sub_f32_e32 v6, v202, v0
	v_mul_f32_e32 v6, 0x3fb8aa3b, v6
	v_sub_f32_e32 v7, v196, v0
	v_exp_f32_e32 v6, v6
	v_mul_f32_e32 v7, 0x3fb8aa3b, v7
	v_sub_f32_e32 v8, v60, v0
	v_exp_f32_e32 v7, v7
	v_mul_f32_e32 v8, 0x3fb8aa3b, v8
	v_sub_f32_e32 v9, v68, v0
	v_exp_f32_e32 v8, v8
	v_mul_f32_e32 v9, 0x3fb8aa3b, v9
	v_exp_f32_e32 v9, v9
	v_add_f32_e32 v10, 0, v6
	v_add_f32_e32 v10, v7, v10
	v_add_f32_e32 v10, v8, v10
	v_add_f32_e32 v10, v9, v10
	v_sub_f32_e32 v0, v67, v0
	v_mul_f32_e32 v0, 0x3fb8aa3b, v0
	v_exp_f32_e32 v0, v0
	v_mov_b32_e32 v2, v10
	v_mov_b32_e32 v3, v10
	s_nop 1
	v_permlane16_swap_b32_e32 v2, v3
	v_add_f32_e32 v1, v2, v3
	s_nop 1
	v_add_f32_dpp v1, v1, v1 quad_perm:[1,0,3,2] row_mask:0xf bank_mask:0xf
	s_nop 1
	v_add_f32_dpp v1, v1, v1 quad_perm:[2,3,0,1] row_mask:0xf bank_mask:0xf
	s_nop 1
	v_add_f32_dpp v1, v1, v1 row_half_mirror row_mask:0xf bank_mask:0xf
	s_nop 1
	v_add_f32_dpp v1, v1, v1 row_mirror row_mask:0xf bank_mask:0xf
	v_add_f32_e32 v0, v0, v1
	v_div_scale_f32 v1, s[4:5], v0, v0, 1.0
	v_rcp_f32_e32 v2, v1
	v_readlane_b32 s4, v254, 43
	v_fma_f32 v3, -v1, v2, 1.0
	v_fmac_f32_e32 v2, v3, v2
	v_div_scale_f32 v3, vcc, 1.0, v0, 1.0
	v_mul_f32_e32 v4, v3, v2
	v_fma_f32 v5, -v1, v4, v3
	v_fmac_f32_e32 v4, v5, v2
	v_fma_f32 v1, -v1, v4, v3
	v_div_fmas_f32 v1, v1, v2, v4
	v_div_fixup_f32 v2, v1, v0, 1.0
	v_lshl_add_u32 v1, v201, 9, s4
	v_lshlrev_b32_e32 v0, 2, v96
	v_mul_f32_e32 v3, v6, v2
	v_add_u32_e32 v4, v1, v0
	v_mul_f32_e32 v5, v7, v2
	ds_write2_b32 v4, v3, v5 offset1:32
	v_mul_f32_e32 v3, v8, v2
	v_mul_f32_e32 v2, v9, v2
	ds_write2_b32 v4, v3, v2 offset0:64 offset1:96
	v_lshl_add_u32 v3, v96, 3, s91
	v_add_u32_e32 v28, 0x8000, v3
	s_waitcnt lgkmcnt(0)
	s_barrier
	ds_read2_b64 v[4:7], v28 offset0:64 offset1:96
	ds_read_b128 v[8:11], v1
	ds_read_b128 v[12:15], v1 offset:16
	ds_read2_b64 v[16:19], v28 offset0:128 offset1:160
	ds_read_b128 v[20:23], v1 offset:32
	ds_read_b128 v[24:27], v1 offset:48
	s_waitcnt lgkmcnt(4)
	v_pk_fma_f32 v[4:5], v[8:9], v[4:5], 0 op_sel_hi:[0,1,0]
	v_pk_fma_f32 v[4:5], v[8:9], v[6:7], v[4:5] op_sel:[1,0,0]
	v_add_u32_e32 v29, 0x8800, v3
	s_waitcnt lgkmcnt(2)
	v_pk_fma_f32 v[16:17], v[10:11], v[16:17], v[4:5] op_sel_hi:[0,1,1]
	ds_read2_b64 v[4:7], v28 offset0:192 offset1:224
	v_mov_b32_e32 v28, v11
	ds_read2_b64 v[8:11], v29 offset1:32
	v_pk_fma_f32 v[16:17], v[28:29], v[18:19], v[16:17] op_sel_hi:[0,1,1]
	v_add_u32_e32 v2, 0x8200, v3
	s_waitcnt lgkmcnt(1)
	v_pk_fma_f32 v[4:5], v[12:13], v[4:5], v[16:17] op_sel_hi:[0,1,1]
	v_pk_fma_f32 v[12:13], v[12:13], v[6:7], v[4:5] op_sel:[1,0,0]
	ds_read2_b64 v[4:7], v29 offset0:64 offset1:96
	ds_read2_b64 v[16:19], v29 offset0:128 offset1:160
	s_waitcnt lgkmcnt(2)
	v_pk_fma_f32 v[8:9], v[14:15], v[8:9], v[12:13] op_sel_hi:[0,1,1]
	v_mov_b32_e32 v12, v15
	v_pk_fma_f32 v[8:9], v[12:13], v[10:11], v[8:9] op_sel_hi:[0,1,1]
	s_waitcnt lgkmcnt(1)
	v_pk_fma_f32 v[4:5], v[20:21], v[4:5], v[8:9] op_sel_hi:[0,1,1]
	v_pk_fma_f32 v[4:5], v[20:21], v[6:7], v[4:5] op_sel:[1,0,0]
	v_mov_b32_e32 v14, v23
	s_waitcnt lgkmcnt(0)
	v_pk_fma_f32 v[12:13], v[22:23], v[16:17], v[4:5] op_sel_hi:[0,1,1]
	ds_read2_b64 v[4:7], v29 offset0:192 offset1:224
	v_add_u32_e32 v22, 0x9000, v3
	ds_read2_b64 v[8:11], v22 offset1:32
	v_pk_fma_f32 v[12:13], v[14:15], v[18:19], v[12:13] op_sel_hi:[0,1,1]
	v_mov_b32_e32 v20, v27
	s_waitcnt lgkmcnt(1)
	v_pk_fma_f32 v[4:5], v[24:25], v[4:5], v[12:13] op_sel_hi:[0,1,1]
	v_pk_fma_f32 v[4:5], v[24:25], v[6:7], v[4:5] op_sel:[1,0,0]
	v_add_u32_e32 v24, 0x9800, v3
	s_waitcnt lgkmcnt(0)
	v_pk_fma_f32 v[8:9], v[26:27], v[8:9], v[4:5] op_sel_hi:[0,1,1]
	ds_read_b128 v[4:7], v1 offset:64
	ds_read2_b64 v[12:15], v22 offset0:64 offset1:96
	ds_read2_b64 v[16:19], v22 offset0:128 offset1:160
	v_pk_fma_f32 v[20:21], v[20:21], v[10:11], v[8:9] op_sel_hi:[0,1,1]
	ds_read_b128 v[8:11], v1 offset:80
	v_add_u32_e32 v26, 0xe000, v3
	s_waitcnt lgkmcnt(2)
	v_pk_fma_f32 v[12:13], v[4:5], v[12:13], v[20:21] op_sel_hi:[0,1,1]
	v_pk_fma_f32 v[4:5], v[4:5], v[14:15], v[12:13] op_sel:[1,0,0]
	ds_read2_b64 v[12:15], v22 offset0:192 offset1:224
	ds_read2_b64 v[20:23], v24 offset1:32
	s_waitcnt lgkmcnt(3)
	v_pk_fma_f32 v[4:5], v[6:7], v[16:17], v[4:5] op_sel_hi:[0,1,1]
	v_mov_b32_e32 v6, v7
	v_pk_fma_f32 v[4:5], v[6:7], v[18:19], v[4:5] op_sel_hi:[0,1,1]
	s_waitcnt lgkmcnt(1)
	v_pk_fma_f32 v[4:5], v[8:9], v[12:13], v[4:5] op_sel_hi:[0,1,1]
	v_pk_fma_f32 v[4:5], v[8:9], v[14:15], v[4:5] op_sel:[1,0,0]
	v_mov_b32_e32 v18, v11
	s_waitcnt lgkmcnt(0)
	v_pk_fma_f32 v[16:17], v[10:11], v[20:21], v[4:5] op_sel_hi:[0,1,1]
	ds_read_b128 v[4:7], v1 offset:96
	ds_read2_b64 v[12:15], v24 offset0:64 offset1:96
	ds_read2_b64 v[8:11], v24 offset0:128 offset1:160
	v_pk_fma_f32 v[20:21], v[18:19], v[22:23], v[16:17] op_sel_hi:[0,1,1]
	ds_read_b128 v[16:19], v1 offset:112
	s_waitcnt lgkmcnt(2)
	v_pk_fma_f32 v[12:13], v[4:5], v[12:13], v[20:21] op_sel_hi:[0,1,1]
	v_pk_fma_f32 v[4:5], v[4:5], v[14:15], v[12:13] op_sel:[1,0,0]
	ds_read2_b64 v[12:15], v24 offset0:192 offset1:224
	v_add_u32_e32 v24, 0xa000, v3
	ds_read2_b64 v[20:23], v24 offset1:32
	s_waitcnt lgkmcnt(3)
	v_pk_fma_f32 v[4:5], v[6:7], v[8:9], v[4:5] op_sel_hi:[0,1,1]
	v_mov_b32_e32 v6, v7
	v_pk_fma_f32 v[4:5], v[6:7], v[10:11], v[4:5] op_sel_hi:[0,1,1]
	s_waitcnt lgkmcnt(1)
	v_pk_fma_f32 v[4:5], v[16:17], v[12:13], v[4:5] op_sel_hi:[0,1,1]
	v_pk_fma_f32 v[4:5], v[16:17], v[14:15], v[4:5] op_sel:[1,0,0]
	s_waitcnt lgkmcnt(0)
	v_pk_fma_f32 v[16:17], v[18:19], v[20:21], v[4:5] op_sel_hi:[0,1,1]
	ds_read_b128 v[4:7], v1 offset:128
	ds_read2_b64 v[8:11], v24 offset0:64 offset1:96
	v_mov_b32_e32 v18, v19
	ds_read2_b64 v[12:15], v24 offset0:128 offset1:160
	v_pk_fma_f32 v[20:21], v[18:19], v[22:23], v[16:17] op_sel_hi:[0,1,1]
	ds_read_b128 v[16:19], v1 offset:144
	s_waitcnt lgkmcnt(2)
	v_pk_fma_f32 v[8:9], v[4:5], v[8:9], v[20:21] op_sel_hi:[0,1,1]
	v_pk_fma_f32 v[4:5], v[4:5], v[10:11], v[8:9] op_sel:[1,0,0]
	ds_read2_b64 v[8:11], v24 offset0:192 offset1:224
	v_add_u32_e32 v24, 0xa800, v3
	ds_read2_b64 v[20:23], v24 offset1:32
	s_waitcnt lgkmcnt(3)
	v_pk_fma_f32 v[4:5], v[6:7], v[12:13], v[4:5] op_sel_hi:[0,1,1]
	v_mov_b32_e32 v6, v7
	v_pk_fma_f32 v[4:5], v[6:7], v[14:15], v[4:5] op_sel_hi:[0,1,1]
	s_waitcnt lgkmcnt(1)
	v_pk_fma_f32 v[4:5], v[16:17], v[8:9], v[4:5] op_sel_hi:[0,1,1]
	v_pk_fma_f32 v[4:5], v[16:17], v[10:11], v[4:5] op_sel:[1,0,0]
	s_waitcnt lgkmcnt(0)
	v_pk_fma_f32 v[16:17], v[18:19], v[20:21], v[4:5] op_sel_hi:[0,1,1]
	ds_read_b128 v[4:7], v1 offset:160
	ds_read2_b64 v[8:11], v24 offset0:64 offset1:96
	v_mov_b32_e32 v18, v19
	ds_read2_b64 v[12:15], v24 offset0:128 offset1:160
	v_pk_fma_f32 v[20:21], v[18:19], v[22:23], v[16:17] op_sel_hi:[0,1,1]
	ds_read_b128 v[16:19], v1 offset:176
	s_waitcnt lgkmcnt(2)
	v_pk_fma_f32 v[8:9], v[4:5], v[8:9], v[20:21] op_sel_hi:[0,1,1]
	v_pk_fma_f32 v[4:5], v[4:5], v[10:11], v[8:9] op_sel:[1,0,0]
	ds_read2_b64 v[8:11], v24 offset0:192 offset1:224
	v_add_u32_e32 v24, 0xb000, v3
	ds_read2_b64 v[20:23], v24 offset1:32
	s_waitcnt lgkmcnt(3)
	v_pk_fma_f32 v[4:5], v[6:7], v[12:13], v[4:5] op_sel_hi:[0,1,1]
	v_mov_b32_e32 v6, v7
	v_pk_fma_f32 v[4:5], v[6:7], v[14:15], v[4:5] op_sel_hi:[0,1,1]
	s_waitcnt lgkmcnt(1)
	v_pk_fma_f32 v[4:5], v[16:17], v[8:9], v[4:5] op_sel_hi:[0,1,1]
	v_pk_fma_f32 v[4:5], v[16:17], v[10:11], v[4:5] op_sel:[1,0,0]
	s_waitcnt lgkmcnt(0)
	v_pk_fma_f32 v[16:17], v[18:19], v[20:21], v[4:5] op_sel_hi:[0,1,1]
	ds_read_b128 v[4:7], v1 offset:192
	ds_read2_b64 v[8:11], v24 offset0:64 offset1:96
	v_mov_b32_e32 v18, v19
	ds_read2_b64 v[12:15], v24 offset0:128 offset1:160
	v_pk_fma_f32 v[20:21], v[18:19], v[22:23], v[16:17] op_sel_hi:[0,1,1]
	ds_read_b128 v[16:19], v1 offset:208
	s_waitcnt lgkmcnt(2)
	v_pk_fma_f32 v[8:9], v[4:5], v[8:9], v[20:21] op_sel_hi:[0,1,1]
	v_pk_fma_f32 v[4:5], v[4:5], v[10:11], v[8:9] op_sel:[1,0,0]
	ds_read2_b64 v[8:11], v24 offset0:192 offset1:224
	v_add_u32_e32 v24, 0xb800, v3
	ds_read2_b64 v[20:23], v24 offset1:32
	s_waitcnt lgkmcnt(3)
	v_pk_fma_f32 v[4:5], v[6:7], v[12:13], v[4:5] op_sel_hi:[0,1,1]
	v_mov_b32_e32 v6, v7
	v_pk_fma_f32 v[4:5], v[6:7], v[14:15], v[4:5] op_sel_hi:[0,1,1]
	s_waitcnt lgkmcnt(1)
	v_pk_fma_f32 v[4:5], v[16:17], v[8:9], v[4:5] op_sel_hi:[0,1,1]
	v_pk_fma_f32 v[4:5], v[16:17], v[10:11], v[4:5] op_sel:[1,0,0]
	s_waitcnt lgkmcnt(0)
	v_pk_fma_f32 v[16:17], v[18:19], v[20:21], v[4:5] op_sel_hi:[0,1,1]
	ds_read_b128 v[4:7], v1 offset:224
	ds_read2_b64 v[8:11], v24 offset0:64 offset1:96
	v_mov_b32_e32 v18, v19
	ds_read2_b64 v[12:15], v24 offset0:128 offset1:160
	v_pk_fma_f32 v[20:21], v[18:19], v[22:23], v[16:17] op_sel_hi:[0,1,1]
	ds_read_b128 v[16:19], v1 offset:240
	s_waitcnt lgkmcnt(2)
	v_pk_fma_f32 v[8:9], v[4:5], v[8:9], v[20:21] op_sel_hi:[0,1,1]
	v_pk_fma_f32 v[4:5], v[4:5], v[10:11], v[8:9] op_sel:[1,0,0]
	ds_read2_b64 v[8:11], v24 offset0:192 offset1:224
	v_add_u32_e32 v24, 0xc000, v3
	ds_read2_b64 v[20:23], v24 offset1:32
	s_waitcnt lgkmcnt(3)
	v_pk_fma_f32 v[4:5], v[6:7], v[12:13], v[4:5] op_sel_hi:[0,1,1]
	v_mov_b32_e32 v6, v7
	v_pk_fma_f32 v[4:5], v[6:7], v[14:15], v[4:5] op_sel_hi:[0,1,1]
	s_waitcnt lgkmcnt(1)
	v_pk_fma_f32 v[4:5], v[16:17], v[8:9], v[4:5] op_sel_hi:[0,1,1]
	v_pk_fma_f32 v[4:5], v[16:17], v[10:11], v[4:5] op_sel:[1,0,0]
	s_waitcnt lgkmcnt(0)
	v_pk_fma_f32 v[16:17], v[18:19], v[20:21], v[4:5] op_sel_hi:[0,1,1]
	ds_read_b128 v[4:7], v1 offset:256
	ds_read2_b64 v[8:11], v24 offset0:64 offset1:96
	v_mov_b32_e32 v18, v19
	ds_read2_b64 v[12:15], v24 offset0:128 offset1:160
	v_pk_fma_f32 v[20:21], v[18:19], v[22:23], v[16:17] op_sel_hi:[0,1,1]
	ds_read_b128 v[16:19], v1 offset:272
	s_waitcnt lgkmcnt(2)
	v_pk_fma_f32 v[8:9], v[4:5], v[8:9], v[20:21] op_sel_hi:[0,1,1]
	v_pk_fma_f32 v[4:5], v[4:5], v[10:11], v[8:9] op_sel:[1,0,0]
	ds_read2_b64 v[8:11], v24 offset0:192 offset1:224
	v_add_u32_e32 v24, 0xc800, v3
	ds_read2_b64 v[20:23], v24 offset1:32
	s_waitcnt lgkmcnt(3)
	v_pk_fma_f32 v[4:5], v[6:7], v[12:13], v[4:5] op_sel_hi:[0,1,1]
	v_mov_b32_e32 v6, v7
	v_pk_fma_f32 v[4:5], v[6:7], v[14:15], v[4:5] op_sel_hi:[0,1,1]
	s_waitcnt lgkmcnt(1)
	v_pk_fma_f32 v[4:5], v[16:17], v[8:9], v[4:5] op_sel_hi:[0,1,1]
	v_pk_fma_f32 v[4:5], v[16:17], v[10:11], v[4:5] op_sel:[1,0,0]
	s_waitcnt lgkmcnt(0)
	v_pk_fma_f32 v[16:17], v[18:19], v[20:21], v[4:5] op_sel_hi:[0,1,1]
	ds_read_b128 v[4:7], v1 offset:288
	ds_read2_b64 v[8:11], v24 offset0:64 offset1:96
	v_mov_b32_e32 v18, v19
	ds_read2_b64 v[12:15], v24 offset0:128 offset1:160
	v_pk_fma_f32 v[20:21], v[18:19], v[22:23], v[16:17] op_sel_hi:[0,1,1]
	ds_read_b128 v[16:19], v1 offset:304
	s_waitcnt lgkmcnt(2)
	v_pk_fma_f32 v[8:9], v[4:5], v[8:9], v[20:21] op_sel_hi:[0,1,1]
	v_pk_fma_f32 v[4:5], v[4:5], v[10:11], v[8:9] op_sel:[1,0,0]
	ds_read2_b64 v[8:11], v24 offset0:192 offset1:224
	v_add_u32_e32 v24, 0xd000, v3
	ds_read2_b64 v[20:23], v24 offset1:32
	s_waitcnt lgkmcnt(3)
	v_pk_fma_f32 v[4:5], v[6:7], v[12:13], v[4:5] op_sel_hi:[0,1,1]
	v_mov_b32_e32 v6, v7
	v_pk_fma_f32 v[4:5], v[6:7], v[14:15], v[4:5] op_sel_hi:[0,1,1]
	s_waitcnt lgkmcnt(1)
	v_pk_fma_f32 v[4:5], v[16:17], v[8:9], v[4:5] op_sel_hi:[0,1,1]
	v_pk_fma_f32 v[4:5], v[16:17], v[10:11], v[4:5] op_sel:[1,0,0]
	s_waitcnt lgkmcnt(0)
	v_pk_fma_f32 v[16:17], v[18:19], v[20:21], v[4:5] op_sel_hi:[0,1,1]
	ds_read_b128 v[4:7], v1 offset:320
	ds_read2_b64 v[8:11], v24 offset0:64 offset1:96
	v_mov_b32_e32 v18, v19
	ds_read2_b64 v[12:15], v24 offset0:128 offset1:160
	v_pk_fma_f32 v[20:21], v[18:19], v[22:23], v[16:17] op_sel_hi:[0,1,1]
	ds_read_b128 v[16:19], v1 offset:336
	s_waitcnt lgkmcnt(2)
	v_pk_fma_f32 v[8:9], v[4:5], v[8:9], v[20:21] op_sel_hi:[0,1,1]
	v_pk_fma_f32 v[4:5], v[4:5], v[10:11], v[8:9] op_sel:[1,0,0]
	ds_read2_b64 v[8:11], v24 offset0:192 offset1:224
	s_waitcnt lgkmcnt(2)
	v_pk_fma_f32 v[4:5], v[6:7], v[12:13], v[4:5] op_sel_hi:[0,1,1]
	v_mov_b32_e32 v6, v7
	v_add_u32_e32 v20, 0xd800, v3
	v_pk_fma_f32 v[12:13], v[6:7], v[14:15], v[4:5] op_sel_hi:[0,1,1]
	ds_read2_b64 v[4:7], v20 offset1:32
	s_waitcnt lgkmcnt(1)
	v_pk_fma_f32 v[8:9], v[16:17], v[8:9], v[12:13] op_sel_hi:[0,1,1]
	v_pk_fma_f32 v[16:17], v[16:17], v[10:11], v[8:9] op_sel:[1,0,0]
	ds_read_b128 v[8:11], v1 offset:352
	ds_read2_b64 v[12:15], v20 offset0:64 offset1:96
	v_lshlrev_b32_e32 v24, 6, v66
	s_waitcnt lgkmcnt(2)
	v_pk_fma_f32 v[4:5], v[18:19], v[4:5], v[16:17] op_sel_hi:[0,1,1]
	v_mov_b32_e32 v16, v19
	v_pk_fma_f32 v[16:17], v[16:17], v[6:7], v[4:5] op_sel_hi:[0,1,1]
	s_waitcnt lgkmcnt(0)
	v_pk_fma_f32 v[12:13], v[8:9], v[12:13], v[16:17] op_sel_hi:[0,1,1]
	v_add_u32_e32 v16, 0x800, v24
	v_lshrrev_b32_e32 v16, 8, v16
	v_mul_hi_i32_i24_e32 v17, 0x4080, v16
	v_mul_i32_i24_e32 v16, 0x4080, v16
	v_lshl_add_u64 v[16:17], v[16:17], 0, v[64:65]
	v_lshlrev_b64 v[16:17], 9, v[16:17]
	v_lshl_add_u64 v[16:17], s[2:3], 0, v[16:17]
	v_lshlrev_b32_e32 v18, 7, v66
	s_movk_i32 s2, 0x180
	v_and_or_b32 v96, v18, s2, v0
	v_lshl_add_u64 v[16:17], v[16:17], 0, v[96:97]
	global_load_dword v25, v[16:17], off
	v_pk_fma_f32 v[8:9], v[8:9], v[14:15], v[12:13] op_sel:[1,0,0]
	ds_read2_b64 v[12:15], v20 offset0:128 offset1:160
	ds_read_b128 v[4:7], v1 offset:368
	ds_read2_b64 v[16:19], v20 offset0:192 offset1:224
	ds_read2_b64 v[20:23], v26 offset1:32
	s_lshl_b32 s2, s36, 12
	s_waitcnt lgkmcnt(3)
	v_pk_fma_f32 v[8:9], v[10:11], v[12:13], v[8:9] op_sel_hi:[0,1,1]
	v_mov_b32_e32 v10, v11
	v_pk_fma_f32 v[8:9], v[10:11], v[14:15], v[8:9] op_sel_hi:[0,1,1]
	s_waitcnt lgkmcnt(1)
	v_pk_fma_f32 v[8:9], v[4:5], v[16:17], v[8:9] op_sel_hi:[0,1,1]
	v_pk_fma_f32 v[4:5], v[4:5], v[18:19], v[8:9] op_sel:[1,0,0]
	ds_read_b128 v[8:11], v1 offset:384
	ds_read2_b64 v[12:15], v26 offset0:64 offset1:96
	s_waitcnt lgkmcnt(2)
	v_pk_fma_f32 v[16:17], v[6:7], v[20:21], v[4:5] op_sel_hi:[0,1,1]
	v_mov_b32_e32 v18, v7
	ds_read2_b64 v[4:7], v26 offset0:128 offset1:160
	v_pk_fma_f32 v[20:21], v[18:19], v[22:23], v[16:17] op_sel_hi:[0,1,1]
	s_waitcnt lgkmcnt(1)
	v_pk_fma_f32 v[12:13], v[8:9], v[12:13], v[20:21] op_sel_hi:[0,1,1]
	ds_read_b128 v[16:19], v1 offset:400
	v_pk_fma_f32 v[8:9], v[8:9], v[14:15], v[12:13] op_sel:[1,0,0]
	ds_read2_b64 v[12:15], v26 offset0:192 offset1:224
	v_add_u32_e32 v26, 0xe800, v3
	ds_read2_b64 v[20:23], v26 offset1:32
	s_waitcnt lgkmcnt(3)
	v_pk_fma_f32 v[4:5], v[10:11], v[4:5], v[8:9] op_sel_hi:[0,1,1]
	v_mov_b32_e32 v8, v11
	v_pk_fma_f32 v[4:5], v[8:9], v[6:7], v[4:5] op_sel_hi:[0,1,1]
	s_waitcnt lgkmcnt(1)
	v_pk_fma_f32 v[4:5], v[16:17], v[12:13], v[4:5] op_sel_hi:[0,1,1]
	v_pk_fma_f32 v[4:5], v[16:17], v[14:15], v[4:5] op_sel:[1,0,0]
	s_add_u32 s0, s0, s2
	s_waitcnt lgkmcnt(0)
	v_pk_fma_f32 v[16:17], v[18:19], v[20:21], v[4:5] op_sel_hi:[0,1,1]
	ds_read_b128 v[4:7], v1 offset:416
	ds_read2_b64 v[8:11], v26 offset0:64 offset1:96
	v_mov_b32_e32 v18, v19
	ds_read2_b64 v[12:15], v26 offset0:128 offset1:160
	v_pk_fma_f32 v[20:21], v[18:19], v[22:23], v[16:17] op_sel_hi:[0,1,1]
	ds_read_b128 v[16:19], v1 offset:432
	s_waitcnt lgkmcnt(2)
	v_pk_fma_f32 v[8:9], v[4:5], v[8:9], v[20:21] op_sel_hi:[0,1,1]
	v_pk_fma_f32 v[4:5], v[4:5], v[10:11], v[8:9] op_sel:[1,0,0]
	ds_read2_b64 v[8:11], v26 offset0:192 offset1:224
	v_add_u32_e32 v26, 0xf000, v3
	ds_read2_b64 v[20:23], v26 offset1:32
	s_waitcnt lgkmcnt(3)
	v_pk_fma_f32 v[4:5], v[6:7], v[12:13], v[4:5] op_sel_hi:[0,1,1]
	v_mov_b32_e32 v6, v7
	v_pk_fma_f32 v[4:5], v[6:7], v[14:15], v[4:5] op_sel_hi:[0,1,1]
	s_waitcnt lgkmcnt(1)
	v_pk_fma_f32 v[4:5], v[16:17], v[8:9], v[4:5] op_sel_hi:[0,1,1]
	v_pk_fma_f32 v[4:5], v[16:17], v[10:11], v[4:5] op_sel:[1,0,0]
	v_add_u32_e32 v3, 0xf800, v3
	s_waitcnt lgkmcnt(0)
	v_pk_fma_f32 v[16:17], v[18:19], v[20:21], v[4:5] op_sel_hi:[0,1,1]
	ds_read_b128 v[4:7], v1 offset:448
	ds_read2_b64 v[8:11], v26 offset0:64 offset1:96
	v_mov_b32_e32 v18, v19
	ds_read2_b64 v[12:15], v26 offset0:128 offset1:160
	v_pk_fma_f32 v[20:21], v[18:19], v[22:23], v[16:17] op_sel_hi:[0,1,1]
	ds_read_b128 v[16:19], v1 offset:464
	s_waitcnt lgkmcnt(2)
	v_pk_fma_f32 v[8:9], v[4:5], v[8:9], v[20:21] op_sel_hi:[0,1,1]
	v_pk_fma_f32 v[4:5], v[4:5], v[10:11], v[8:9] op_sel:[1,0,0]
	ds_read2_b64 v[8:11], v26 offset0:192 offset1:224
	ds_read2_b64 v[20:23], v3 offset1:32
	s_waitcnt lgkmcnt(3)
	v_pk_fma_f32 v[4:5], v[6:7], v[12:13], v[4:5] op_sel_hi:[0,1,1]
	v_mov_b32_e32 v6, v7
	v_pk_fma_f32 v[4:5], v[6:7], v[14:15], v[4:5] op_sel_hi:[0,1,1]
	s_waitcnt lgkmcnt(1)
	v_pk_fma_f32 v[4:5], v[16:17], v[8:9], v[4:5] op_sel_hi:[0,1,1]
	v_pk_fma_f32 v[4:5], v[16:17], v[10:11], v[4:5] op_sel:[1,0,0]
	s_addc_u32 s1, s1, 0
	s_waitcnt lgkmcnt(0)
	v_pk_fma_f32 v[16:17], v[18:19], v[20:21], v[4:5] op_sel_hi:[0,1,1]
	ds_read_b128 v[4:7], v1 offset:480
	ds_read2_b64 v[8:11], v3 offset0:64 offset1:96
	v_mov_b32_e32 v18, v19
	ds_read2_b64 v[12:15], v3 offset0:128 offset1:160
	v_pk_fma_f32 v[20:21], v[18:19], v[22:23], v[16:17] op_sel_hi:[0,1,1]
	ds_read_b128 v[16:19], v1 offset:496
	s_waitcnt lgkmcnt(2)
	v_pk_fma_f32 v[8:9], v[4:5], v[8:9], v[20:21] op_sel_hi:[0,1,1]
	v_pk_fma_f32 v[4:5], v[4:5], v[10:11], v[8:9] op_sel:[1,0,0]
	ds_read2_b64 v[8:11], v3 offset0:192 offset1:224
	v_add_u32_e32 v1, 0x7800, v2
	s_waitcnt lgkmcnt(2)
	v_pk_fma_f32 v[12:13], v[6:7], v[12:13], v[4:5] op_sel_hi:[0,1,1]
	ds_read2_b64 v[2:5], v1 offset0:192 offset1:224
	v_mov_b32_e32 v6, v7
	v_pk_fma_f32 v[6:7], v[6:7], v[14:15], v[12:13] op_sel_hi:[0,1,1]
	s_waitcnt lgkmcnt(1)
	v_pk_fma_f32 v[6:7], v[16:17], v[8:9], v[6:7] op_sel_hi:[0,1,1]
	v_pk_fma_f32 v[6:7], v[16:17], v[10:11], v[6:7] op_sel:[1,0,0]
	v_mov_b32_e32 v1, v97
	s_waitcnt lgkmcnt(0)
	v_pk_fma_f32 v[2:3], v[18:19], v[2:3], v[6:7] op_sel_hi:[0,1,1]
	v_mov_b32_e32 v6, v19
	v_pk_fma_f32 v[2:3], v[6:7], v[4:5], v[2:3] op_sel_hi:[0,1,1]
	s_waitcnt vmcnt(0)
	v_lshlrev_b32_e32 v4, 16, v25
	v_and_b32_e32 v5, 0xffff0000, v25
	v_pk_mul_f32 v[2:3], v[2:3], v[4:5]
	v_ashrrev_i32_e32 v25, 31, v24
	v_cvt_pk_bf16_f32 v4, v2, v3
	v_lshl_add_u64 v[2:3], v[24:25], 1, s[0:1]
	v_lshl_add_u64 v[0:1], v[2:3], 0, v[0:1]
	v_add_co_u32_e32 v0, vcc, 0x15860000, v0
	s_mov_b64 s[0:1], 0
	s_nop 0
	v_addc_co_u32_e32 v1, vcc, 0, v1, vcc
	global_store_dword v[0:1], v4, off
